# prompt diff-attention inner loop software-pipelined: PV of tile t-1 interleaved with softmax of tile t, P kept in registers across the barrier, DMA distance 2
# speedup vs baseline: 1.0034x; 1.0012x over previous
; __device__ __forceinline__ int pi32(int r) { return (r & ~12) | ((r & 4) << 1) | ((r & 8) >> 1); }
; #define AT_DMA(tr) do { const unsigned sb_ = (unsigned)__builtin_amdgcn_readfirstlane(dk + (((tr) & (NSTG - 1)) * STAGE)); const size_t ko_ = (size_t)(tr) * 26 * 4096, vo_ = (size_t)(tr) * 640 * 64; \
;         glds16(kg + ko_, sb_ + OFF_K0); if (!WIN) glds16(kg + ko_ + 4096, sb_ + OFF_K1); glds16(vg + vo_, sb_ + OFF_V); if (!WIN) glds16(vg + vo_ + 64 * 64, sb_ + OFF_V + 8192); } while (0)
; template <bool WIN> ...
;     ...
;     const bf16_t* kg = QK + ((size_t)((seq_base >> 6) + t_lo) * 26 * 64 + drow) * 64 + dch * 8 + kcol0 * 64;
;     const bf16_t* vg = VT + ((size_t)((seq_base >> 6) + t_lo) * 640 + vrow0 + drow) * 64 + dch * 8;
;     const unsigned dk = ldsb + wid * 1024;
;     ...
;     constexpr int NPW = WIN ? 2 : 4;
;     bf16x8 qfr[4];
;     { const int qrow = seq_base + qw + l31; const bf16_t* qp = QK + ((size_t)((qrow >> 6) * 26 + (qcol >> 6)) * 64 + (qrow & 63)) * 64 + hi * 8;
; #pragma unroll
;       for (int ds = 0; ds < 4; ++ds) qfr[ds] = *(const bf16x8*)(qp + ds * 16); }
;     ...
;     AT_DMA(0); if (NT > 1) AT_DMA(1); if (NT > 2) AT_DMA(2);
;     constexpr float THR = 8.0f;
;     float m_ref = WIN ? sinkp[2 * hsel + half] * LOG2E : 0.f;
;     float l_run = (WIN && hi == 0) ? 1.f : 0.f;
;     float cbase = 0.f;
;     f32x16 cvec;
; #pragma unroll
;     for (int r = 0; r < 16; ++r) cvec[r] = cbase - m_ref;
;     f32x16 o[NDB];
; #pragma unroll
;     for (int db = 0; db < NDB; ++db)
; #pragma unroll
;         for (int r = 0; r < 16; ++r) o[db][r] = 0.f;
;     const int krow = pi32(l31), fK = (krow >> 1) & 7, fV = (l31 >> 1) & 7;
;     int kx[4], vx[4];
; #pragma unroll
;     for (int c = 0; c < 4; ++c) { kx[c] = (WIN ? OFF_K0 : (half ? OFF_K1 : OFF_K0)) + krow * 128 + (((2 * c + hi) ^ fK) << 4); vx[c] = OFF_V + l31 * 128 + (((2 * c + hi) ^ fV) << 4); }
.LBB0_244:
	s_lshl_b32 s62, s33, 5
	s_lshl_b32 s20, s33, 2
	s_and_b32 s62, s62, 32
	v_readfirstlane_b32 s64, v230
	s_and_b32 s20, s20, 24
	s_add_i32 s62, s62, s22
	s_bfe_u32 s77, s64, 0x20006
	s_or_b32 s20, s20, s24
	s_lshl_b32 s62, s62, 7
	s_lshl_b32 s82, s77, 5
	s_lshl_b32 s20, s20, 11
	s_or_b32 s78, s82, s62
	s_and_b32 s20, s20, 0xe000
	s_lshr_b32 s76, s64, 8
	v_or_b32_e32 v4, s78, v185
	v_add_u32_e32 v170, s20, v4
	s_add_i32 s62, s76, s66
	v_ashrrev_i32_e32 v2, 6, v170
	v_mov_b32_e32 v0, s62
	v_mad_u64_u32 v[2:3], s[62:63], v2, 26, v[0:1]
	v_ashrrev_i32_e32 v3, 31, v2
	v_lshlrev_b64 v[2:3], 13, v[2:3]
	v_lshlrev_b32_e32 v0, 7, v4
	v_lshl_add_u64 v[2:3], s[6:7], 0, v[2:3]
	v_and_b32_e32 v4, 0x1f80, v0
	v_mov_b32_e32 v5, v1
	v_lshl_add_u64 v[2:3], v[2:3], 0, v[4:5]
	v_lshl_add_u64 v[2:3], v[2:3], 0, v[164:165]
	global_load_dwordx4 v[114:117], v[2:3], off offset:96
	global_load_dwordx4 v[118:121], v[2:3], off offset:64
	global_load_dwordx4 v[122:125], v[2:3], off offset:32
	global_load_dwordx4 v[126:129], v[2:3], off
	s_lshl_b32 s62, s31, 11
	s_and_b32 s62, s62, 0xffffc000
	s_or_b32 s62, s26, s62
	v_cndmask_b32_e64 v0, 0, 1, s[38:39]
	s_lshr_b32 s81, s62, 13
	v_readfirstlane_b32 s62, v0
	s_lshr_b32 s63, s64, 4
	s_lshl_b32 s83, s62, 12
	s_lshr_b32 s62, s64, 6
	s_and_b32 s63, s63, 4
	s_lshl_b32 s84, s62, 3
	v_bitop3_b32 v4, s63, v186, v189 bitop3:0x36
	s_lshr_b32 s63, s20, 6
	v_or_b32_e32 v0, s84, v188
	s_mul_i32 s20, s63, 0x680
	v_lshl_add_u64 v[2:3], s[20:21], 0, v[0:1]
	v_lshlrev_b64 v[2:3], 7, v[2:3]
	v_lshl_add_u64 v[2:3], s[6:7], 0, v[2:3]
	v_lshlrev_b32_e32 v4, 4, v4
	v_lshl_add_u64 v[2:3], v[2:3], 0, v[4:5]
	s_mul_i32 s20, s63, 0x280
	v_add_u32_e32 v6, s12, v0
	v_mov_b32_e32 v7, v1
	v_lshl_add_u64 v[2:3], v[2:3], 0, s[18:19]
	v_lshl_add_u64 v[6:7], v[6:7], 0, s[20:21]
	s_lshl_b32 s20, s62, 10
	s_mov_b64 s[62:63], 0x24000
	v_lshl_add_u64 v[8:9], v[2:3], 0, s[62:63]
	s_add_i32 s20, s20, 0
	s_mov_b32 s62, m0
	s_mov_b32 m0, s20
	s_nop 0
	global_load_lds_dwordx4 v[8:9], off
	s_mov_b32 m0, s62
	s_mov_b64 s[62:63], 0x26000
	v_lshlrev_b64 v[6:7], 7, v[6:7]
	v_lshl_add_u64 v[8:9], v[2:3], 0, s[62:63]
	s_add_i32 s62, s20, 0x2000
	v_lshl_add_u64 v[6:7], s[4:5], 0, v[6:7]
	s_mov_b32 s63, m0
	s_mov_b32 m0, s62
	s_nop 0
	global_load_lds_dwordx4 v[8:9], off
	s_mov_b32 m0, s63
	s_add_i32 s62, s20, 0x4000
	v_lshl_add_u64 v[6:7], v[6:7], 0, v[4:5]
	s_mov_b32 s63, m0
	s_mov_b32 m0, s62
	s_nop 0
	global_load_lds_dwordx4 v[6:7], off
	s_mov_b32 m0, s63
	s_add_i32 s62, s20, 0x6000
	v_lshl_add_u64 v[8:9], v[6:7], 0, s[40:41]
	s_mov_b32 s63, m0
	s_mov_b32 m0, s62
	s_nop 0
	global_load_lds_dwordx4 v[8:9], off
	s_mov_b32 m0, s63
	s_add_i32 s62, s20, 0x8000
	v_lshl_add_u64 v[8:9], v[2:3], 0, s[42:43]
	s_mov_b32 s63, m0
	s_mov_b32 m0, s62
	s_nop 0
	global_load_lds_dwordx4 v[8:9], off
	s_mov_b32 m0, s63
	s_add_i32 s62, s20, 0xa000
	v_lshl_add_u64 v[8:9], v[2:3], 0, s[46:47]
	s_mov_b32 s63, m0
	s_mov_b32 m0, s62
	s_nop 0
	global_load_lds_dwordx4 v[8:9], off
	s_mov_b32 m0, s63
	s_add_i32 s62, s20, 0xc000
	v_lshl_add_u64 v[8:9], v[6:7], 0, s[48:49]
	s_mov_b32 s63, m0
	s_mov_b32 m0, s62
	s_nop 0
	global_load_lds_dwordx4 v[8:9], off
	s_mov_b32 m0, s63
	s_add_i32 s62, s20, 0xe000
	v_lshl_add_u64 v[8:9], v[6:7], 0, s[50:51]
	s_mov_b32 s63, m0
	s_mov_b32 m0, s62
	s_nop 0
	global_load_lds_dwordx4 v[8:9], off
	s_mov_b32 m0, s63
	s_add_i32 s62, s20, 0x10000
	v_lshl_add_u64 v[8:9], v[2:3], 0, s[52:53]
	s_add_i32 s62, s20, 0x12000
	v_lshl_add_u64 v[2:3], v[2:3], 0, s[54:55]
	s_add_i32 s62, s20, 0x14000
	v_lshl_add_u64 v[2:3], v[6:7], 0, s[56:57]
	s_add_i32 s62, s20, 0x16000
	v_lshl_add_u64 v[2:3], v[6:7], 0, s[58:59]
	s_cmpk_lt_u32 s64, 0x100
	s_cselect_b64 s[62:63], -1, 0
	s_and_b64 s[64:65], s[62:63], exec
	s_cselect_b32 s64, 0, 0x2000
	s_add_i32 s67, s27, 0x20000
	v_mov_b32_e32 v2, s67
	ds_read_b32 v3, v2 offset:14336
	ds_read_b32 v2, v2 offset:16124
	v_or_b32_e32 v162, s64, v177
	v_mov_b32_e32 v14, v1
	v_mov_b32_e32 v15, v1
	s_waitcnt lgkmcnt(1)
	v_readfirstlane_b32 s79, v3
	s_waitcnt lgkmcnt(0)
	v_readfirstlane_b32 s80, v2
	v_add_u32_e32 v2, s84, v197
	v_mov_b32_e32 v3, v1
	v_lshlrev_b64 v[2:3], 7, v[2:3]
	v_mad_u64_u32 v[2:3], s[64:65], s81, v199, v[2:3]
	v_or_b32_e32 v2, v2, v4
	v_lshl_add_u64 v[172:173], s[36:37], 0, v[2:3]
	v_lshlrev_b64 v[2:3], 7, v[0:1]
	v_mad_u64_u32 v[2:3], s[64:65], s81, v200, v[2:3]
	s_or_b32 s64, s82, s83
	v_or_b32_e32 v2, v2, v4
	v_add_lshl_u32 v0, s64, v198, 2
	v_lshl_add_u64 v[174:175], s[16:17], 0, v[2:3]
	v_sub_u32_e32 v171, v195, v0
	s_sub_i32 s64, s28, s82
	v_mov_b32_e32 v0, v1
	v_mov_b32_e32 v2, v1
	v_mov_b32_e32 v3, v1
	v_mov_b32_e32 v4, v1
	v_mov_b32_e32 v6, v1
	v_mov_b32_e32 v7, v1
	v_mov_b32_e32 v8, v1
	v_mov_b32_e32 v9, v1
	v_mov_b32_e32 v10, v1
	v_mov_b32_e32 v11, v1
	v_mov_b32_e32 v12, v1
	v_mov_b32_e32 v13, v1
	v_mov_b64_e32 v[64:65], v[14:15]
	v_mov_b64_e32 v[48:49], v[14:15]
	v_mov_b64_e32 v[32:33], v[14:15]
	s_sub_i32 s81, s64, s83
	s_add_i32 s64, s29, s83
	v_mov_b64_e32 v[62:63], v[12:13]
	v_mov_b64_e32 v[60:61], v[10:11]
	v_mov_b64_e32 v[58:59], v[8:9]
	v_mov_b64_e32 v[56:57], v[6:7]
	v_mov_b64_e32 v[54:55], v[4:5]
	v_mov_b64_e32 v[52:53], v[2:3]
	v_mov_b64_e32 v[50:51], v[0:1]
	v_mov_b64_e32 v[46:47], v[12:13]
	v_mov_b64_e32 v[44:45], v[10:11]
	v_mov_b64_e32 v[42:43], v[8:9]
	v_mov_b64_e32 v[40:41], v[6:7]
	v_mov_b64_e32 v[38:39], v[4:5]
	v_mov_b64_e32 v[36:37], v[2:3]
	v_mov_b64_e32 v[34:35], v[0:1]
	v_mov_b64_e32 v[30:31], v[12:13]
	v_mov_b64_e32 v[28:29], v[10:11]
	v_mov_b64_e32 v[26:27], v[8:9]
	v_mov_b64_e32 v[24:25], v[6:7]
	v_mov_b64_e32 v[22:23], v[4:5]
	v_mov_b64_e32 v[20:21], v[2:3]
	v_mov_b64_e32 v[18:19], v[0:1]
	v_mov_b64_e32 v[16:17], v[14:15]
	s_add_i32 s82, s64, s82
	s_mov_b32 s83, 0
	s_mov_b32 s84, 0
	s_mov_b32 s85, 0x10000
	v_mov_b64_e32 v[14:15], v[12:13]
	v_mov_b64_e32 v[12:13], v[10:11]
	v_mov_b64_e32 v[10:11], v[8:9]
	v_mov_b64_e32 v[8:9], v[6:7]
	v_mov_b64_e32 v[6:7], v[4:5]
	v_mov_b64_e32 v[4:5], v[2:3]
	v_mov_b64_e32 v[2:3], v[0:1]
	v_mov_b32_e32 v0, 0
	v_mov_b32_e32 v196, 0
	v_mov_b32_e32 v202, 0
	s_mov_b32 s86, 0
	v_mov_b32_e32 v66, 0
	v_mov_b32_e32 v67, v1
	v_mov_b32_e32 v68, v1
	v_mov_b32_e32 v69, v1
	v_mov_b32_e32 v70, v1
	v_mov_b32_e32 v71, v1
	v_mov_b32_e32 v72, v1
	v_mov_b32_e32 v73, v1
	v_mov_b32_e32 v74, v1
	v_mov_b32_e32 v75, v1
	v_mov_b32_e32 v76, v1
	v_mov_b32_e32 v77, v1
	v_mov_b32_e32 v78, v1
	v_mov_b32_e32 v79, v1
	v_mov_b32_e32 v80, v1
	v_mov_b32_e32 v81, v1
	s_mov_b32 s98, 0xfffec000
	s_mov_b32 s99, -1
	v_lshl_add_u64 v[172:173], v[172:173], 0, s[98:99]
	s_mov_b32 s98, 0xfffcc000
	s_waitcnt vmcnt(8)
	v_lshl_add_u64 v[174:175], v[174:175], 0, s[98:99]
	s_branch .LSPp_top
; #define ALAS __attribute__((address_space(3)))
; template <bool WIN> ...
;     ...
;     for (int tr = 0; tr < NT; ++tr) {
;         if (tr + 2 < NT) wait_bar<2 * NPW>(); else if (tr + 1 < NT) wait_bar<NPW>(); else wait_bar<0>();
;         if (tr + 3 < NT) AT_DMA(tr + 3);
;         const int k0 = (t_lo + tr) * 64;
;         const bool skip = WIN && (k0 > qw + 31 + 128 || k0 + 63 < qw - 128);
;         if (!skip) {
;             const bool near = WIN || ((k0 - (qw + 31)) < 128 && (qw - (k0 + 63)) < 128);
;             const float cinit = near ? 0.f : (k0 > qw ? cfar_hi : cfar_lo);
;             if (__builtin_expect(cinit != cbase, 0)) { cbase = cinit; asm volatile("" ::: "memory");
; #pragma unroll
;                 for (int r = 0; r < 16; ++r) cvec[r] = cbase - m_ref; }
;             f32x16 s0, s1;
;             const ALAS unsigned char* sb = lds + (tr & (NSTG - 1)) * STAGE;
;             {
;                 bf16x8 ka[8];
; #pragma unroll
;                 for (int ds = 0; ds < 4; ++ds) { ka[2 * ds] = *(const ALAS bf16x8*)(sb + kx[ds]); ka[2 * ds + 1] = *(const ALAS bf16x8*)(sb + kx[ds] + 4096); }
;                 __builtin_amdgcn_sched_barrier(0);
;                 s0 = __builtin_amdgcn_mfma_f32_32x32x16_bf16(ka[0], qf(0), cvec, 0, 0, 0);
;                 s1 = __builtin_amdgcn_mfma_f32_32x32x16_bf16(ka[1], qf(0), cvec, 0, 0, 0);
; #pragma unroll
;                 for (int ds = 1; ds < 4; ++ds) {
;                     s0 = __builtin_amdgcn_mfma_f32_32x32x16_bf16(ka[2 * ds], qf(ds), s0, 0, 0, 0);
;                     s1 = __builtin_amdgcn_mfma_f32_32x32x16_bf16(ka[2 * ds + 1], qf(ds), s1, 0, 0, 0);
;                 }
;             }
;             bf16x8 va[2 * NDB], vc[2 * NDB];
; #pragma unroll
;             for (int kk = 0; kk < 2; ++kk)
; #pragma unroll
;                 for (int db = 0; db < NDB; ++db) va[kk * NDB + db] = *(const ALAS bf16x8*)(sb + vx[kk] + db * 4096);
;             __builtin_amdgcn_sched_barrier(0);
;             if (near) {
;                 const ALAS float* lb = lut + (k0 + 8 * hi - qabs + LUTC);
; #pragma unroll
;                 for (int r = 0; r < 16; ++r) { s0[r] += lb[16 * (r >> 3) + (r & 7)]; s1[r] += lb[32 + 16 * (r >> 3) + (r & 7)];
;                     if ((r & 7) == 7) __builtin_amdgcn_sched_barrier(0); }
;             }
.LSPp_top:
	s_cmpk_gt_u32 s86, 126
	s_cbranch_scc1 .LSPp_t0
	s_waitcnt vmcnt(4) lgkmcnt(0)
	s_barrier
.LSPp_t0d:
	s_cmpk_gt_u32 s86, 125
	s_cbranch_scc1 .LSPp_nodma
	s_and_b32 s98, s85, 0x18000
	s_add_i32 s98, s98, s20
	s_mov_b32 m0, s98
	v_lshl_add_u64 v[82:83], v[174:175], 0, s[40:41]
	global_load_lds_dwordx4 v[174:175], off
	s_add_i32 m0, s98, 0x2000
	s_nop 0
	global_load_lds_dwordx4 v[82:83], off
	s_add_i32 m0, s98, 0x4000
	v_lshl_add_u64 v[82:83], v[172:173], 0, s[40:41]
	global_load_lds_dwordx4 v[172:173], off
	s_add_i32 m0, s98, 0x6000
	s_nop 0
	global_load_lds_dwordx4 v[82:83], off
.LSPp_nodma:
.LSPp_scal:
	s_add_i32 s64, s81, s83
	s_max_i32 s64, s64, s82
	s_cmpk_lt_i32 s64, 0x80
	s_cselect_b64 s[64:65], -1, 0
	s_cmp_gt_i32 s83, s78
	s_cselect_b32 s87, s80, s79
	v_mov_b32_e32 v82, s87
	v_cndmask_b32_e64 v98, v82, 0, s[64:65]
	v_cmp_eq_f32_e32 vcc, v98, v202
	s_nop 1
	s_and_b64 vcc, exec, vcc
	s_cbranch_vccz .LSPp_cin
.LSPp_qk:
	s_add_i32 s87, s85, 0xffff0000
	s_and_b32 s87, s87, 0x18000
	s_add_i32 s99, s85, 0xfffe8000
	s_and_b32 s99, s99, 0x18000
	v_add3_u32 v203, s87, v178, v162
	ds_read_b128 v[130:133], v203
	ds_read_b128 v[134:137], v203 offset:4096
	v_add3_u32 v203, s87, v180, v162
	ds_read_b128 v[138:141], v203
	ds_read_b128 v[142:145], v203 offset:4096
	v_add3_u32 v203, s87, v182, v162
	ds_read_b128 v[146:149], v203
	ds_read_b128 v[150:153], v203 offset:4096
	v_add3_u32 v203, s87, v184, v162
	ds_read_b128 v[158:161], v203
	ds_read_b128 v[204:207], v203 offset:4096
	s_waitcnt lgkmcnt(0)
	v_mfma_f32_32x32x16_bf16 v[98:113], v[130:133], v[126:129], v[66:81]
	v_mfma_f32_32x32x16_bf16 v[82:97], v[134:137], v[126:129], v[66:81]
	v_mfma_f32_32x32x16_bf16 v[98:113], v[138:141], v[122:125], v[98:113]
	v_mfma_f32_32x32x16_bf16 v[82:97], v[142:145], v[122:125], v[82:97]
	v_mfma_f32_32x32x16_bf16 v[98:113], v[146:149], v[118:121], v[98:113]
	v_mfma_f32_32x32x16_bf16 v[82:97], v[150:153], v[118:121], v[82:97]
	v_mfma_f32_32x32x16_bf16 v[98:113], v[158:161], v[114:117], v[98:113]
	v_mfma_f32_32x32x16_bf16 v[82:97], v[204:207], v[114:117], v[82:97]
	v_add3_u32 v236, s99, v179, v187
	ds_read_b128 v[146:149], v236 offset:16384
	ds_read_b128 v[150:153], v236 offset:20480
	ds_read_b128 v[154:157], v236 offset:24576
	ds_read_b128 v[158:161], v236 offset:28672
	v_add3_u32 v237, s99, v181, v187
	ds_read_b128 v[130:133], v237 offset:16384
	ds_read_b128 v[134:137], v237 offset:20480
	ds_read_b128 v[138:141], v237 offset:24576
	ds_read_b128 v[142:145], v237 offset:28672
	s_nop 1
	s_andn2_b64 vcc, exec, s[64:65]
	s_cbranch_vccnz .LSPp_max
	v_add_u32_e32 v203, s84, v171
	v_add_u32_e32 v204, 0x23b80, v203
	v_add_u32_e32 v206, 0x23c00, v203
	v_add_u32_e32 v210, 0x23c08, v203
	v_add_u32_e32 v208, 0x23b88, v203
	v_add_u32_e32 v218, 0x23c10, v203
	v_add_u32_e32 v212, 0x23b90, v203
	v_add_u32_e32 v216, 0x23c18, v203
	v_add_u32_e32 v214, 0x23b98, v203
	ds_read2_b32 v[204:205], v204 offset1:1
	ds_read2_b32 v[206:207], v206 offset1:1
	ds_read2_b32 v[208:209], v208 offset1:1
	ds_read2_b32 v[210:211], v210 offset1:1
	ds_read2_b32 v[212:213], v212 offset1:1
	ds_read2_b32 v[214:215], v214 offset1:1
	ds_read2_b32 v[216:217], v216 offset1:1
	ds_read2_b32 v[218:219], v218 offset1:1
	v_add_u32_e32 v220, 0x23bc0, v203
	v_add_u32_e32 v222, 0x23c40, v203
	v_add_u32_e32 v226, 0x23c48, v203
	v_add_u32_e32 v224, 0x23bc8, v203
	v_add_u32_e32 v228, 0x23bd0, v203
	v_add_u32_e32 v234, 0x23c58, v203
	ds_read2_b32 v[220:221], v220 offset1:1
	ds_read2_b32 v[222:223], v222 offset1:1
	ds_read2_b32 v[224:225], v224 offset1:1
	ds_read2_b32 v[226:227], v226 offset1:1
	v_add_u32_e32 v231, 0x23c50, v203
	v_add_u32_e32 v203, 0x23bd8, v203
	ds_read2_b32 v[228:229], v228 offset1:1
	ds_read2_b32 v[232:233], v203 offset1:1
	ds_read2_b32 v[234:235], v234 offset1:1
	ds_read2_b32 v[236:237], v231 offset1:1
	s_waitcnt lgkmcnt(10)
	v_pk_add_f32 v[104:105], v[104:105], v[214:215]
	v_pk_add_f32 v[102:103], v[102:103], v[212:213]
	v_pk_add_f32 v[100:101], v[100:101], v[208:209]
	s_waitcnt lgkmcnt(2)
	v_pk_add_f32 v[112:113], v[112:113], v[232:233]
	v_pk_add_f32 v[110:111], v[110:111], v[228:229]
	v_pk_add_f32 v[108:109], v[108:109], v[224:225]
	v_pk_add_f32 v[106:107], v[106:107], v[220:221]
	v_pk_add_f32 v[98:99], v[98:99], v[204:205]
	v_pk_add_f32 v[88:89], v[88:89], v[216:217]
	v_pk_add_f32 v[86:87], v[86:87], v[218:219]
	v_pk_add_f32 v[84:85], v[84:85], v[210:211]
	s_waitcnt lgkmcnt(1)
	v_pk_add_f32 v[96:97], v[96:97], v[234:235]
	s_waitcnt lgkmcnt(0)
	v_pk_add_f32 v[94:95], v[94:95], v[236:237]
	v_pk_add_f32 v[92:93], v[92:93], v[226:227]
	v_pk_add_f32 v[90:91], v[90:91], v[222:223]
	v_pk_add_f32 v[82:83], v[82:83], v[206:207]
; #define MX3(a, b, c) __builtin_fmaxf(__builtin_fmaxf((a), (b)), (c))
; template <bool WIN> ...
;     ...
;             float mxa = MX3(s0[0], s0[1], s1[0]), mxb = MX3(s0[2], s0[3], s1[1]);
;             mxa = MX3(mxa, s1[2], s1[3]);
; #pragma unroll
;             for (int r = 4; r < 16; r += 4) { mxa = MX3(mxa, s0[r], s0[r + 1]); mxb = MX3(mxb, s0[r + 2], s0[r + 3]); mxa = MX3(mxa, s1[r], s1[r + 1]); mxb = MX3(mxb, s1[r + 2], s1[r + 3]); }
;     ...
;             float mx = fmaxf(mxa, mxb);
;             if (__any(mx > THR)) {
;                 mx = fmaxf(mx, __shfl_xor(mx, 32));
;                 const float dl = fmaxf(mx, 0.f);
;                 m_ref += dl;
;                 const float f = __builtin_amdgcn_exp2f(-dl);
;                 l_run *= f;
; #pragma unroll
;                 for (int db = 0; db < NDB; ++db)
; #pragma unroll
;                     for (int r = 0; r < 16; ++r) o[db][r] *= f;
; #pragma unroll
;                 for (int r = 0; r < 16; ++r) { s0[r] -= dl; s1[r] -= dl; cvec[r] = cbase - m_ref; }
;             }
;     ...
;             for (int db = 0; db < NDB; ++db) o[db] = __builtin_amdgcn_mfma_f32_32x32x16_bf16(va[db], p0.b, o[db], 0, 0, 0);
;             AT_EXP(s0, 8, p1);
;             __builtin_amdgcn_sched_barrier(0);
; #pragma unroll
;             for (int db = 0; db < NDB; ++db) o[db] = __builtin_amdgcn_mfma_f32_32x32x16_bf16(va[NDB + db], p1.b, o[db], 0, 0, 0);
;             AT_EXP(s1, 0, p2);
;             __builtin_amdgcn_sched_barrier(0);
; #pragma unroll
;             for (int db = 0; db < NDB; ++db) o[db] = __builtin_amdgcn_mfma_f32_32x32x16_bf16(vc[db], p2.b, o[db], 0, 0, 0);
;             AT_EXP(s1, 8, p3);
;             __builtin_amdgcn_sched_barrier(0);
; #pragma unroll
;             for (int db = 0; db < NDB; ++db) o[db] = __builtin_amdgcn_mfma_f32_32x32x16_bf16(vc[NDB + db], p3.b, o[db], 0, 0, 0);
.LSPp_max:
	s_nop 0
	v_max_f32_e32 v203, v99, v99
	v_max_f32_e32 v204, v98, v98
	v_max_f32_e32 v203, v204, v203
	s_nop 5
	v_max3_f32 v204, v100, v101, v83
	v_max3_f32 v203, v203, v82, v84
	v_max3_f32 v203, v203, v85, v102
	v_max3_f32 v204, v204, v104, v105
	v_max3_f32 v203, v203, v103, v86
	v_max3_f32 v204, v204, v88, v89
	v_max3_f32 v203, v203, v87, v106
	v_max3_f32 v204, v204, v108, v109
	v_max3_f32 v203, v203, v107, v90
	v_max3_f32 v204, v204, v92, v93
	v_max3_f32 v203, v203, v91, v110
	v_max3_f32 v204, v204, v112, v113
	v_max3_f32 v203, v203, v111, v94
	v_max3_f32 v204, v204, v96, v97
	v_max3_f32 v203, v203, v95, v204
	v_cmp_lt_f32_e32 vcc, s30, v203
	s_cbranch_vccz .LSPp_pv
	s_cmp_eq_u32 s86, 0
	s_cbranch_scc1 .LSPp_rnopv
	s_waitcnt lgkmcnt(0)
	v_add3_u32 v236, s99, v179, v187
	ds_read_b128 v[146:149], v236 offset:16384
	ds_read_b128 v[150:153], v236 offset:20480
	ds_read_b128 v[154:157], v236 offset:24576
	ds_read_b128 v[158:161], v236 offset:28672
	v_add3_u32 v237, s99, v181, v187
	ds_read_b128 v[130:133], v237 offset:16384
	ds_read_b128 v[134:137], v237 offset:20480
	ds_read_b128 v[138:141], v237 offset:24576
	ds_read_b128 v[142:145], v237 offset:28672
	s_waitcnt lgkmcnt(4)
	v_mfma_f32_32x32x16_bf16 v[50:65], v[146:149], v[238:241], v[50:65]
	v_mfma_f32_32x32x16_bf16 v[34:49], v[150:153], v[238:241], v[34:49]
	v_mfma_f32_32x32x16_bf16 v[18:33], v[154:157], v[238:241], v[18:33]
	v_mfma_f32_32x32x16_bf16 v[2:17], v[158:161], v[238:241], v[2:17]
	v_add3_u32 v236, s99, v183, v187
	ds_read_b128 v[146:149], v236 offset:16384
	ds_read_b128 v[150:153], v236 offset:20480
	ds_read_b128 v[154:157], v236 offset:24576
	ds_read_b128 v[158:161], v236 offset:28672
	s_waitcnt lgkmcnt(4)
	v_mfma_f32_32x32x16_bf16 v[50:65], v[130:133], v[242:245], v[50:65]
	v_mfma_f32_32x32x16_bf16 v[34:49], v[134:137], v[242:245], v[34:49]
	v_mfma_f32_32x32x16_bf16 v[18:33], v[138:141], v[242:245], v[18:33]
	v_mfma_f32_32x32x16_bf16 v[2:17], v[142:145], v[242:245], v[2:17]
	v_add3_u32 v237, s99, v190, v187
	ds_read_b128 v[130:133], v237 offset:16384
	ds_read_b128 v[134:137], v237 offset:20480
	ds_read_b128 v[138:141], v237 offset:24576
	ds_read_b128 v[142:145], v237 offset:28672
	s_waitcnt lgkmcnt(4)
	v_mfma_f32_32x32x16_bf16 v[50:65], v[146:149], v[246:249], v[50:65]
	v_mfma_f32_32x32x16_bf16 v[34:49], v[150:153], v[246:249], v[34:49]
	v_mfma_f32_32x32x16_bf16 v[18:33], v[154:157], v[246:249], v[18:33]
	v_mfma_f32_32x32x16_bf16 v[2:17], v[158:161], v[246:249], v[2:17]
	s_waitcnt lgkmcnt(0)
	v_mfma_f32_32x32x16_bf16 v[50:65], v[130:133], v[250:253], v[50:65]
	v_mfma_f32_32x32x16_bf16 v[34:49], v[134:137], v[250:253], v[34:49]
	v_mfma_f32_32x32x16_bf16 v[18:33], v[138:141], v[250:253], v[18:33]
	v_mfma_f32_32x32x16_bf16 v[2:17], v[142:145], v[250:253], v[2:17]
.LSPp_rnopv:
	ds_bpermute_b32 v66, v176, v203
	s_waitcnt lgkmcnt(0)
	v_max3_f32 v68, v203, v66, 0
	v_exp_f32_e64 v70, -v68
	v_add_f32_e32 v196, v196, v68
	v_sub_f32_e32 v66, v202, v196
	v_pk_add_f32 v[98:99], v[98:99], v[68:69] op_sel_hi:[1,0] neg_lo:[0,1] neg_hi:[0,1]
	v_pk_mul_f32 v[64:65], v[64:65], v[70:71] op_sel_hi:[1,0]
	v_pk_mul_f32 v[62:63], v[62:63], v[70:71] op_sel_hi:[1,0]
	v_pk_mul_f32 v[60:61], v[60:61], v[70:71] op_sel_hi:[1,0]
	v_pk_mul_f32 v[58:59], v[58:59], v[70:71] op_sel_hi:[1,0]
	v_pk_mul_f32 v[56:57], v[56:57], v[70:71] op_sel_hi:[1,0]
	v_pk_mul_f32 v[54:55], v[54:55], v[70:71] op_sel_hi:[1,0]
	v_pk_mul_f32 v[52:53], v[52:53], v[70:71] op_sel_hi:[1,0]
	v_pk_mul_f32 v[50:51], v[50:51], v[70:71] op_sel_hi:[1,0]
	v_pk_mul_f32 v[48:49], v[48:49], v[70:71] op_sel_hi:[1,0]
	v_pk_mul_f32 v[46:47], v[46:47], v[70:71] op_sel_hi:[1,0]
	v_pk_mul_f32 v[44:45], v[44:45], v[70:71] op_sel_hi:[1,0]
	v_pk_mul_f32 v[42:43], v[42:43], v[70:71] op_sel_hi:[1,0]
	v_pk_mul_f32 v[40:41], v[40:41], v[70:71] op_sel_hi:[1,0]
	v_pk_mul_f32 v[38:39], v[38:39], v[70:71] op_sel_hi:[1,0]
	v_pk_mul_f32 v[36:37], v[36:37], v[70:71] op_sel_hi:[1,0]
	v_pk_mul_f32 v[34:35], v[34:35], v[70:71] op_sel_hi:[1,0]
	v_pk_mul_f32 v[32:33], v[32:33], v[70:71] op_sel_hi:[1,0]
	v_pk_mul_f32 v[30:31], v[30:31], v[70:71] op_sel_hi:[1,0]
	v_pk_mul_f32 v[28:29], v[28:29], v[70:71] op_sel_hi:[1,0]
	v_pk_mul_f32 v[26:27], v[26:27], v[70:71] op_sel_hi:[1,0]
	v_pk_mul_f32 v[24:25], v[24:25], v[70:71] op_sel_hi:[1,0]
	v_pk_mul_f32 v[22:23], v[22:23], v[70:71] op_sel_hi:[1,0]
	v_pk_mul_f32 v[20:21], v[20:21], v[70:71] op_sel_hi:[1,0]
	v_pk_mul_f32 v[18:19], v[18:19], v[70:71] op_sel_hi:[1,0]
	v_pk_mul_f32 v[16:17], v[16:17], v[70:71] op_sel_hi:[1,0]
	v_pk_mul_f32 v[14:15], v[14:15], v[70:71] op_sel_hi:[1,0]
	v_pk_mul_f32 v[12:13], v[12:13], v[70:71] op_sel_hi:[1,0]
	v_pk_mul_f32 v[10:11], v[10:11], v[70:71] op_sel_hi:[1,0]
	v_pk_mul_f32 v[8:9], v[8:9], v[70:71] op_sel_hi:[1,0]
	v_pk_mul_f32 v[6:7], v[6:7], v[70:71] op_sel_hi:[1,0]
	v_pk_mul_f32 v[4:5], v[4:5], v[70:71] op_sel_hi:[1,0]
	v_pk_mul_f32 v[2:3], v[2:3], v[70:71] op_sel_hi:[1,0]
	v_pk_add_f32 v[82:83], v[82:83], v[68:69] op_sel_hi:[1,0] neg_lo:[0,1] neg_hi:[0,1]
	v_pk_add_f32 v[100:101], v[100:101], v[68:69] op_sel_hi:[1,0] neg_lo:[0,1] neg_hi:[0,1]
	v_pk_add_f32 v[84:85], v[84:85], v[68:69] op_sel_hi:[1,0] neg_lo:[0,1] neg_hi:[0,1]
	v_pk_add_f32 v[102:103], v[102:103], v[68:69] op_sel_hi:[1,0] neg_lo:[0,1] neg_hi:[0,1]
	v_pk_add_f32 v[86:87], v[86:87], v[68:69] op_sel_hi:[1,0] neg_lo:[0,1] neg_hi:[0,1]
	v_pk_add_f32 v[104:105], v[104:105], v[68:69] op_sel_hi:[1,0] neg_lo:[0,1] neg_hi:[0,1]
	v_pk_add_f32 v[88:89], v[88:89], v[68:69] op_sel_hi:[1,0] neg_lo:[0,1] neg_hi:[0,1]
	v_pk_add_f32 v[106:107], v[106:107], v[68:69] op_sel_hi:[1,0] neg_lo:[0,1] neg_hi:[0,1]
	v_pk_add_f32 v[90:91], v[90:91], v[68:69] op_sel_hi:[1,0] neg_lo:[0,1] neg_hi:[0,1]
	v_pk_add_f32 v[108:109], v[108:109], v[68:69] op_sel_hi:[1,0] neg_lo:[0,1] neg_hi:[0,1]
	v_pk_add_f32 v[92:93], v[92:93], v[68:69] op_sel_hi:[1,0] neg_lo:[0,1] neg_hi:[0,1]
	v_pk_add_f32 v[110:111], v[110:111], v[68:69] op_sel_hi:[1,0] neg_lo:[0,1] neg_hi:[0,1]
	v_pk_add_f32 v[94:95], v[94:95], v[68:69] op_sel_hi:[1,0] neg_lo:[0,1] neg_hi:[0,1]
	v_pk_add_f32 v[112:113], v[112:113], v[68:69] op_sel_hi:[1,0] neg_lo:[0,1] neg_hi:[0,1]
	v_pk_add_f32 v[96:97], v[96:97], v[68:69] op_sel_hi:[1,0] neg_lo:[0,1] neg_hi:[0,1]
	v_mul_f32_e32 v0, v0, v70
	v_mov_b32_e32 v67, v66
	v_mov_b32_e32 v68, v66
	v_mov_b32_e32 v69, v66
	v_mov_b32_e32 v70, v66
	v_mov_b32_e32 v71, v66
	v_mov_b32_e32 v72, v66
	v_mov_b32_e32 v73, v66
	v_mov_b32_e32 v74, v66
	v_mov_b32_e32 v75, v66
	v_mov_b32_e32 v76, v66
	v_mov_b32_e32 v77, v66
	v_mov_b32_e32 v78, v66
	v_mov_b32_e32 v79, v66
	v_mov_b32_e32 v80, v66
	v_mov_b32_e32 v81, v66
	s_branch .LSPp_pure
; #define ALAS __attribute__((address_space(3)))
; template <bool WIN> ...
;     ...
;             float ls0 = 0.f, ls1 = 0.f;
;     ...
;             union PFU { u32x4 u; bf16x8 b; };
;             PFU p0, p1, p2, p3;
;             AT_EXP(s0, 0, p0);
; #pragma unroll
;             for (int kk = 0; kk < 2; ++kk)
; #pragma unroll
;                 for (int db = 0; db < NDB; ++db) vc[kk * NDB + db] = *(const ALAS bf16x8*)(sb + vx[kk + 2] + db * 4096);
;             __builtin_amdgcn_sched_barrier(0);
; #pragma unroll
;             for (int db = 0; db < NDB; ++db) o[db] = __builtin_amdgcn_mfma_f32_32x32x16_bf16(va[db], p0.b, o[db], 0, 0, 0);
;             AT_EXP(s0, 8, p1);
;             __builtin_amdgcn_sched_barrier(0);
; #pragma unroll
;             for (int db = 0; db < NDB; ++db) o[db] = __builtin_amdgcn_mfma_f32_32x32x16_bf16(va[NDB + db], p1.b, o[db], 0, 0, 0);
;             AT_EXP(s1, 0, p2);
;             __builtin_amdgcn_sched_barrier(0);
; #pragma unroll
;             for (int db = 0; db < NDB; ++db) o[db] = __builtin_amdgcn_mfma_f32_32x32x16_bf16(vc[db], p2.b, o[db], 0, 0, 0);
;             AT_EXP(s1, 8, p3);
;             __builtin_amdgcn_sched_barrier(0);
; #pragma unroll
;             for (int db = 0; db < NDB; ++db) o[db] = __builtin_amdgcn_mfma_f32_32x32x16_bf16(vc[NDB + db], p3.b, o[db], 0, 0, 0);
;             __builtin_amdgcn_sched_barrier(0);
;     ...
;             l_run += ls0 + ls1;
.LSPp_pv:
	s_cmp_eq_u32 s86, 0
	s_cbranch_scc1 .LSPp_pure
	v_mov_b32_e32 v228, 0
	v_mov_b32_e32 v229, 0
	s_waitcnt lgkmcnt(4)
	v_mfma_f32_32x32x16_bf16 v[50:65], v[146:149], v[238:241], v[50:65]
	v_exp_f32_e32 v98, v98
	v_exp_f32_e32 v99, v99
	v_mfma_f32_32x32x16_bf16 v[34:49], v[150:153], v[238:241], v[34:49]
	v_exp_f32_e32 v100, v100
	v_exp_f32_e32 v101, v101
	v_add_f32_e32 v228, v228, v98
	v_add_f32_e32 v229, v229, v99
	v_mfma_f32_32x32x16_bf16 v[18:33], v[154:157], v[238:241], v[18:33]
	v_exp_f32_e32 v102, v102
	v_exp_f32_e32 v103, v103
	v_add_f32_e32 v228, v228, v100
	v_add_f32_e32 v229, v229, v101
	v_mfma_f32_32x32x16_bf16 v[2:17], v[158:161], v[238:241], v[2:17]
	v_exp_f32_e32 v104, v104
	v_exp_f32_e32 v105, v105
	v_add_f32_e32 v228, v228, v102
	v_add_f32_e32 v229, v229, v103
	v_add3_u32 v236, s99, v183, v187
	ds_read_b128 v[146:149], v236 offset:16384
	ds_read_b128 v[150:153], v236 offset:20480
	ds_read_b128 v[154:157], v236 offset:24576
	ds_read_b128 v[158:161], v236 offset:28672
	s_waitcnt lgkmcnt(4)
	v_mfma_f32_32x32x16_bf16 v[50:65], v[130:133], v[242:245], v[50:65]
	v_exp_f32_e32 v106, v106
	v_exp_f32_e32 v107, v107
	v_add_f32_e32 v228, v228, v104
	v_add_f32_e32 v229, v229, v105
	v_cvt_pk_bf16_f32 v238, v98, v99
	v_mfma_f32_32x32x16_bf16 v[34:49], v[134:137], v[242:245], v[34:49]
	v_exp_f32_e32 v108, v108
	v_exp_f32_e32 v109, v109
	v_add_f32_e32 v228, v228, v106
	v_add_f32_e32 v229, v229, v107
	v_cvt_pk_bf16_f32 v239, v100, v101
	v_mfma_f32_32x32x16_bf16 v[18:33], v[138:141], v[242:245], v[18:33]
	v_exp_f32_e32 v110, v110
	v_exp_f32_e32 v111, v111
	v_add_f32_e32 v228, v228, v108
	v_add_f32_e32 v229, v229, v109
	v_cvt_pk_bf16_f32 v240, v102, v103
	v_mfma_f32_32x32x16_bf16 v[2:17], v[142:145], v[242:245], v[2:17]
	v_exp_f32_e32 v112, v112
	v_exp_f32_e32 v113, v113
	v_add_f32_e32 v228, v228, v110
	v_add_f32_e32 v229, v229, v111
	v_cvt_pk_bf16_f32 v241, v104, v105
	v_add3_u32 v237, s99, v190, v187
	ds_read_b128 v[130:133], v237 offset:16384
	ds_read_b128 v[134:137], v237 offset:20480
	ds_read_b128 v[138:141], v237 offset:24576
	ds_read_b128 v[142:145], v237 offset:28672
	s_waitcnt lgkmcnt(4)
	v_mfma_f32_32x32x16_bf16 v[50:65], v[146:149], v[246:249], v[50:65]
	v_exp_f32_e32 v82, v82
	v_exp_f32_e32 v83, v83
	v_add_f32_e32 v228, v228, v112
	v_add_f32_e32 v229, v229, v113
	v_cvt_pk_bf16_f32 v242, v106, v107
	v_mfma_f32_32x32x16_bf16 v[34:49], v[150:153], v[246:249], v[34:49]
	v_exp_f32_e32 v84, v84
	v_exp_f32_e32 v85, v85
	v_add_f32_e32 v228, v228, v82
	v_add_f32_e32 v229, v229, v83
	v_cvt_pk_bf16_f32 v243, v108, v109
	v_mfma_f32_32x32x16_bf16 v[18:33], v[154:157], v[246:249], v[18:33]
	v_exp_f32_e32 v86, v86
	v_exp_f32_e32 v87, v87
	v_add_f32_e32 v228, v228, v84
	v_add_f32_e32 v229, v229, v85
	v_cvt_pk_bf16_f32 v244, v110, v111
	v_mfma_f32_32x32x16_bf16 v[2:17], v[158:161], v[246:249], v[2:17]
	v_exp_f32_e32 v88, v88
	v_exp_f32_e32 v89, v89
	v_add_f32_e32 v228, v228, v86
	v_add_f32_e32 v229, v229, v87
	v_cvt_pk_bf16_f32 v245, v112, v113
	s_waitcnt lgkmcnt(0)
	v_mfma_f32_32x32x16_bf16 v[50:65], v[130:133], v[250:253], v[50:65]
	v_exp_f32_e32 v90, v90
	v_exp_f32_e32 v91, v91
	v_add_f32_e32 v228, v228, v88
	v_add_f32_e32 v229, v229, v89
	v_cvt_pk_bf16_f32 v246, v82, v83
	v_mfma_f32_32x32x16_bf16 v[34:49], v[134:137], v[250:253], v[34:49]
	v_exp_f32_e32 v92, v92
	v_exp_f32_e32 v93, v93
	v_add_f32_e32 v228, v228, v90
	v_add_f32_e32 v229, v229, v91
	v_cvt_pk_bf16_f32 v247, v84, v85
	v_mfma_f32_32x32x16_bf16 v[18:33], v[138:141], v[250:253], v[18:33]
	v_exp_f32_e32 v94, v94
	v_exp_f32_e32 v95, v95
	v_add_f32_e32 v228, v228, v92
	v_add_f32_e32 v229, v229, v93
	v_cvt_pk_bf16_f32 v248, v86, v87
	v_mfma_f32_32x32x16_bf16 v[2:17], v[142:145], v[250:253], v[2:17]
	v_exp_f32_e32 v96, v96
	v_exp_f32_e32 v97, v97
	v_add_f32_e32 v228, v228, v94
	v_add_f32_e32 v229, v229, v95
	v_cvt_pk_bf16_f32 v249, v88, v89
	v_add_f32_e32 v228, v228, v96
	v_add_f32_e32 v229, v229, v97
	v_cvt_pk_bf16_f32 v250, v90, v91
	v_cvt_pk_bf16_f32 v251, v92, v93
	v_cvt_pk_bf16_f32 v252, v94, v95
	v_cvt_pk_bf16_f32 v253, v96, v97
	v_add_f32_e32 v228, v228, v229
	s_add_i32 s86, s86, 1
	s_add_i32 s85, s85, 0x8000
	s_addk_i32 s84, 0x100
	s_add_i32 s83, s83, 64
	s_sub_i32 s82, s82, 64
	v_add_f32_e32 v0, v0, v228
	v_lshl_add_u64 v[172:173], v[172:173], 0, s[48:49]
	s_cmpk_eq_u32 s84, 0x8000
	v_lshl_add_u64 v[174:175], v[174:175], 0, s[60:61]
	s_cbranch_scc0 .LSPp_top
	s_branch .LSPp_exit
; #define ALAS __attribute__((address_space(3)))
; template <bool WIN> ...
;     ...
;             const float cinit = near ? 0.f : (k0 > qw ? cfar_hi : cfar_lo);
;             if (__builtin_expect(cinit != cbase, 0)) { cbase = cinit; asm volatile("" ::: "memory");
; #pragma unroll
;                 for (int r = 0; r < 16; ++r) cvec[r] = cbase - m_ref; }
;     ...
;             float ls0 = 0.f, ls1 = 0.f;
;     ...
;             union PFU { u32x4 u; bf16x8 b; };
;             PFU p0, p1, p2, p3;
;             AT_EXP(s0, 0, p0);
; #pragma unroll
;             for (int kk = 0; kk < 2; ++kk)
; #pragma unroll
;                 for (int db = 0; db < NDB; ++db) vc[kk * NDB + db] = *(const ALAS bf16x8*)(sb + vx[kk + 2] + db * 4096);
;             __builtin_amdgcn_sched_barrier(0);
; #pragma unroll
;             for (int db = 0; db < NDB; ++db) o[db] = __builtin_amdgcn_mfma_f32_32x32x16_bf16(va[db], p0.b, o[db], 0, 0, 0);
;             AT_EXP(s0, 8, p1);
;             __builtin_amdgcn_sched_barrier(0);
; #pragma unroll
;             for (int db = 0; db < NDB; ++db) o[db] = __builtin_amdgcn_mfma_f32_32x32x16_bf16(va[NDB + db], p1.b, o[db], 0, 0, 0);
;             AT_EXP(s1, 0, p2);
;             __builtin_amdgcn_sched_barrier(0);
; #pragma unroll
;             for (int db = 0; db < NDB; ++db) o[db] = __builtin_amdgcn_mfma_f32_32x32x16_bf16(vc[db], p2.b, o[db], 0, 0, 0);
;             AT_EXP(s1, 8, p3);
;             __builtin_amdgcn_sched_barrier(0);
; #pragma unroll
;             for (int db = 0; db < NDB; ++db) o[db] = __builtin_amdgcn_mfma_f32_32x32x16_bf16(vc[NDB + db], p3.b, o[db], 0, 0, 0);
;             __builtin_amdgcn_sched_barrier(0);
;     ...
;             l_run += ls0 + ls1;
.LSPp_pure:
	v_exp_f32_e32 v98, v98
	v_exp_f32_e32 v99, v99
	v_exp_f32_e32 v100, v100
	v_exp_f32_e32 v101, v101
	v_exp_f32_e32 v102, v102
	v_exp_f32_e32 v103, v103
	v_exp_f32_e32 v104, v104
	v_exp_f32_e32 v105, v105
	v_cvt_pk_bf16_f32 v238, v98, v99
	v_cvt_pk_bf16_f32 v239, v100, v101
	v_cvt_pk_bf16_f32 v240, v102, v103
	v_cvt_pk_bf16_f32 v241, v104, v105
	v_mov_b32_e32 v228, v98
	v_mov_b32_e32 v229, v102
	v_add_f32_e32 v228, v228, v99
	v_add_f32_e32 v229, v229, v103
	v_add_f32_e32 v228, v228, v100
	v_add_f32_e32 v229, v229, v104
	v_add_f32_e32 v228, v228, v101
	v_add_f32_e32 v229, v229, v105
	v_exp_f32_e32 v106, v106
	v_exp_f32_e32 v107, v107
	v_exp_f32_e32 v108, v108
	v_exp_f32_e32 v109, v109
	v_exp_f32_e32 v110, v110
	v_exp_f32_e32 v111, v111
	v_exp_f32_e32 v112, v112
	v_exp_f32_e32 v113, v113
	v_cvt_pk_bf16_f32 v242, v106, v107
	v_cvt_pk_bf16_f32 v243, v108, v109
	v_cvt_pk_bf16_f32 v244, v110, v111
	v_cvt_pk_bf16_f32 v245, v112, v113
	v_add_f32_e32 v228, v228, v106
	v_add_f32_e32 v229, v229, v110
	v_add_f32_e32 v228, v228, v107
	v_add_f32_e32 v229, v229, v111
	v_add_f32_e32 v228, v228, v108
	v_add_f32_e32 v229, v229, v112
	v_add_f32_e32 v228, v228, v109
	v_add_f32_e32 v229, v229, v113
	v_exp_f32_e32 v82, v82
	v_exp_f32_e32 v83, v83
	v_exp_f32_e32 v84, v84
	v_exp_f32_e32 v85, v85
	v_exp_f32_e32 v86, v86
	v_exp_f32_e32 v87, v87
	v_exp_f32_e32 v88, v88
	v_exp_f32_e32 v89, v89
	v_cvt_pk_bf16_f32 v246, v82, v83
	v_cvt_pk_bf16_f32 v247, v84, v85
	v_cvt_pk_bf16_f32 v248, v86, v87
	v_cvt_pk_bf16_f32 v249, v88, v89
	v_add_f32_e32 v228, v228, v82
	v_add_f32_e32 v229, v229, v86
	v_add_f32_e32 v228, v228, v83
	v_add_f32_e32 v229, v229, v87
	v_add_f32_e32 v228, v228, v84
	v_add_f32_e32 v229, v229, v88
	v_add_f32_e32 v228, v228, v85
	v_add_f32_e32 v229, v229, v89
	v_exp_f32_e32 v90, v90
	v_exp_f32_e32 v91, v91
	v_exp_f32_e32 v92, v92
	v_exp_f32_e32 v93, v93
	v_exp_f32_e32 v94, v94
	v_exp_f32_e32 v95, v95
	v_exp_f32_e32 v96, v96
	v_exp_f32_e32 v97, v97
	v_cvt_pk_bf16_f32 v250, v90, v91
	v_cvt_pk_bf16_f32 v251, v92, v93
	v_cvt_pk_bf16_f32 v252, v94, v95
	v_cvt_pk_bf16_f32 v253, v96, v97
	v_add_f32_e32 v228, v228, v90
	v_add_f32_e32 v229, v229, v94
	v_add_f32_e32 v228, v228, v91
	v_add_f32_e32 v229, v229, v95
	v_add_f32_e32 v228, v228, v92
	v_add_f32_e32 v229, v229, v96
	v_add_f32_e32 v228, v228, v93
	v_add_f32_e32 v229, v229, v97
	v_add_f32_e32 v228, v228, v229
	s_add_i32 s86, s86, 1
	s_add_i32 s85, s85, 0x8000
	s_addk_i32 s84, 0x100
	s_add_i32 s83, s83, 64
	s_sub_i32 s82, s82, 64
	v_add_f32_e32 v0, v0, v228
	v_lshl_add_u64 v[172:173], v[172:173], 0, s[48:49]
	s_cmpk_eq_u32 s84, 0x8000
	v_lshl_add_u64 v[174:175], v[174:175], 0, s[60:61]
	s_cbranch_scc0 .LSPp_top
	s_branch .LSPp_exit
.LSPp_exit:
	s_add_i32 s99, s85, 0xfffe8000
	s_and_b32 s99, s99, 0x18000
	v_add3_u32 v236, s99, v179, v187
	ds_read_b128 v[146:149], v236 offset:16384
	ds_read_b128 v[150:153], v236 offset:20480
	ds_read_b128 v[154:157], v236 offset:24576
	ds_read_b128 v[158:161], v236 offset:28672
	v_add3_u32 v237, s99, v181, v187
	ds_read_b128 v[130:133], v237 offset:16384
	ds_read_b128 v[134:137], v237 offset:20480
	ds_read_b128 v[138:141], v237 offset:24576
	ds_read_b128 v[142:145], v237 offset:28672
	s_waitcnt lgkmcnt(4)
	v_mfma_f32_32x32x16_bf16 v[50:65], v[146:149], v[238:241], v[50:65]
	v_mfma_f32_32x32x16_bf16 v[34:49], v[150:153], v[238:241], v[34:49]
	v_mfma_f32_32x32x16_bf16 v[18:33], v[154:157], v[238:241], v[18:33]
	v_mfma_f32_32x32x16_bf16 v[2:17], v[158:161], v[238:241], v[2:17]
	v_add3_u32 v236, s99, v183, v187
	ds_read_b128 v[146:149], v236 offset:16384
	ds_read_b128 v[150:153], v236 offset:20480
	ds_read_b128 v[154:157], v236 offset:24576
	ds_read_b128 v[158:161], v236 offset:28672
	s_waitcnt lgkmcnt(4)
	v_mfma_f32_32x32x16_bf16 v[50:65], v[130:133], v[242:245], v[50:65]
	v_mfma_f32_32x32x16_bf16 v[34:49], v[134:137], v[242:245], v[34:49]
	v_mfma_f32_32x32x16_bf16 v[18:33], v[138:141], v[242:245], v[18:33]
	v_mfma_f32_32x32x16_bf16 v[2:17], v[142:145], v[242:245], v[2:17]
	v_add3_u32 v237, s99, v190, v187
	ds_read_b128 v[130:133], v237 offset:16384
	ds_read_b128 v[134:137], v237 offset:20480
	ds_read_b128 v[138:141], v237 offset:24576
	ds_read_b128 v[142:145], v237 offset:28672
	s_waitcnt lgkmcnt(4)
	v_mfma_f32_32x32x16_bf16 v[50:65], v[146:149], v[246:249], v[50:65]
	v_mfma_f32_32x32x16_bf16 v[34:49], v[150:153], v[246:249], v[34:49]
	v_mfma_f32_32x32x16_bf16 v[18:33], v[154:157], v[246:249], v[18:33]
	v_mfma_f32_32x32x16_bf16 v[2:17], v[158:161], v[246:249], v[2:17]
	s_waitcnt lgkmcnt(0)
	v_mfma_f32_32x32x16_bf16 v[50:65], v[130:133], v[250:253], v[50:65]
	v_mfma_f32_32x32x16_bf16 v[34:49], v[134:137], v[250:253], v[34:49]
	v_mfma_f32_32x32x16_bf16 v[18:33], v[138:141], v[250:253], v[18:33]
	v_mfma_f32_32x32x16_bf16 v[2:17], v[142:145], v[250:253], v[2:17]
	s_branch .LBB0_262
.LSPp_t0:
	s_waitcnt vmcnt(0) lgkmcnt(0)
	s_barrier
	s_branch .LSPp_t0d
.LSPp_cin:
	v_sub_f32_e32 v82, v98, v196
	v_mov_b32_e32 v202, v98
	v_mov_b32_e32 v66, v82
	v_mov_b32_e32 v67, v82
	v_mov_b32_e32 v68, v82
	v_mov_b32_e32 v69, v82
	v_mov_b32_e32 v70, v82
	v_mov_b32_e32 v71, v82
	v_mov_b32_e32 v72, v82
	v_mov_b32_e32 v73, v82
	v_mov_b32_e32 v74, v82
	v_mov_b32_e32 v75, v82
	v_mov_b32_e32 v76, v82
	v_mov_b32_e32 v77, v82
	v_mov_b32_e32 v78, v82
	v_mov_b32_e32 v79, v82
	v_mov_b32_e32 v80, v82
	v_mov_b32_e32 v81, v82
	s_branch .LSPp_qk
